# E31: pool fast path v2: 4 rows/iteration, ds_read_u16_d16_hi widening, immediate offsets, scalar trip count; exact 2^-(g+1) multiply; on E27
# baseline (speedup 1.0000x reference)
.Lpoolfast_setup:
	s_add_i32 s46, s58, 1
	s_lshl_b32 s46, s46, 23
	s_sub_i32 s46, 0x3f800000, s46
	v_readfirstlane_b32 s47, v6
	s_sub_i32 s47, s51, s47
	s_min_i32 s47, s47, 32
	s_waitcnt lgkmcnt(0)
	v_mov_b32_e32 v14, 0
	v_mov_b32_e32 v15, 0
	v_mov_b32_e32 v16, 0
	v_mov_b32_e32 v17, 0
	v_mov_b32_e32 v20, 0
	v_mov_b32_e32 v21, 0
	v_mov_b32_e32 v11, 0
	v_mov_b32_e32 v18, 0
.Lpoolfast_loop:
	ds_read_u16_d16_hi v14, v8
	ds_read_u16_d16_hi v15, v19 offset:272
	ds_read_u16_d16_hi v16, v8 offset:272
	ds_read_u16_d16_hi v17, v19 offset:544
	ds_read_u16_d16_hi v20, v8 offset:544
	ds_read_u16_d16_hi v21, v19 offset:816
	ds_read_u16_d16_hi v11, v8 offset:816
	ds_read_u16_d16_hi v18, v19 offset:1088
	s_waitcnt lgkmcnt(6)
	v_add_f32_e32 v9, v9, v14
	v_mul_f32_e32 v12, s46, v9
	v_sub_f32_e32 v13, v12, v14
	v_cvt_pk_bf16_f32 v13, v13, s0
	ds_write_b16 v8, v13 offset:35088
	v_sub_f32_e32 v9, v9, v15
	s_waitcnt lgkmcnt(5)
	v_add_f32_e32 v9, v9, v16
	v_mul_f32_e32 v12, s46, v9
	v_sub_f32_e32 v13, v12, v16
	v_cvt_pk_bf16_f32 v13, v13, s0
	ds_write_b16 v8, v13 offset:35360
	v_sub_f32_e32 v9, v9, v17
	s_waitcnt lgkmcnt(4)
	v_add_f32_e32 v9, v9, v20
	v_mul_f32_e32 v12, s46, v9
	v_sub_f32_e32 v13, v12, v20
	v_cvt_pk_bf16_f32 v13, v13, s0
	ds_write_b16 v8, v13 offset:35632
	v_sub_f32_e32 v9, v9, v21
	s_waitcnt lgkmcnt(3)
	v_add_f32_e32 v9, v9, v11
	v_mul_f32_e32 v12, s46, v9
	v_sub_f32_e32 v13, v12, v11
	v_cvt_pk_bf16_f32 v13, v13, s0
	ds_write_b16 v8, v13 offset:35904
	v_sub_f32_e32 v9, v9, v18
	v_add_u32_e32 v8, 0x440, v8
	v_add_u32_e32 v19, 0x440, v19
	s_add_i32 s47, s47, -4
	s_cmp_gt_i32 s47, 0
	s_cbranch_scc1 .Lpoolfast_loop
	s_branch .LBB0_487
